# gated LayerNorm gate loops: 4 interleaved ds_bpermute butterflies per trip replaced by DPP + readlane reductions
# speedup vs baseline: 1.0061x; 1.0015x over previous
.LBB0_304:
	ds_read_b128 v[108:111], v201
	ds_read_b128 v[64:67], v201 offset:16
	ds_read_b128 v[88:91], v201 offset:2048
	ds_read_b128 v[68:71], v201 offset:2064
	ds_read_b128 v[84:87], v201 offset:4096
	ds_read_b128 v[72:75], v201 offset:4112
	ds_read_b128 v[80:83], v201 offset:6144
	ds_read_b128 v[76:79], v201 offset:6160
	ds_read_b128 v[124:127], v201 offset:8192
	ds_read_b128 v[92:95], v201 offset:8208
	ds_read_b128 v[120:123], v201 offset:10240
	ds_read_b128 v[96:99], v201 offset:10256
	ds_read_b128 v[116:119], v201 offset:12288
	ds_read_b128 v[100:103], v201 offset:12304
	ds_read_b128 v[112:115], v201 offset:14336
	ds_read_b128 v[104:107], v201 offset:14352
	ds_read_b128 v[202:205], v201 offset:16384
	ds_read_b128 v[128:131], v201 offset:16400
	ds_read_b128 v[206:209], v201 offset:18432
	ds_read_b128 v[132:135], v201 offset:18448
	ds_read_b128 v[148:151], v201 offset:20480
	ds_read_b128 v[136:139], v201 offset:20496
	ds_read_b128 v[144:147], v201 offset:22528
	ds_read_b128 v[140:143], v201 offset:22544
	s_waitcnt lgkmcnt(14)
	v_mov_b32_e32 v211, v64
	v_mov_b32_e32 v64, v109
	v_mov_b32_e32 v109, v66
	v_mov_b32_e32 v66, v111
	ds_read_b128 v[214:217], v201 offset:24576
	ds_read_b128 v[218:221], v201 offset:24592
	ds_read_b128 v[222:225], v201 offset:26624
	ds_read_b128 v[226:229], v201 offset:26640
	ds_read_b128 v[230:233], v201 offset:28672
	ds_read_b128 v[234:237], v201 offset:28688
	ds_read_b128 v[238:241], v201 offset:30720
	ds_read_b128 v[242:245], v201 offset:30736
	v_mov_b32_e32 v210, v108
	v_mov_b32_e32 v108, v110
	v_mov_b32_e32 v111, v68
	v_mov_b32_e32 v68, v89
	v_mov_b32_e32 v89, v70
	v_mov_b32_e32 v70, v91
	v_mov_b32_e32 v91, v72
	v_mov_b32_e32 v72, v85
	v_mov_b32_e32 v85, v74
	v_mov_b32_e32 v74, v87
	v_mov_b32_e32 v87, v76
	v_mov_b32_e32 v76, v81
	v_mov_b32_e32 v81, v78
	v_mov_b32_e32 v78, v83
	v_mov_b32_e32 v83, v92
	v_mov_b32_e32 v92, v125
	v_mov_b32_e32 v125, v94
	v_mov_b32_e32 v94, v127
	s_waitcnt lgkmcnt(14)
	v_mov_b32_e32 v127, v96
	v_mov_b32_e32 v96, v121
	v_mov_b32_e32 v121, v98
	v_mov_b32_e32 v98, v123
	v_mov_b32_e32 v123, v100
	v_mov_b32_e32 v100, v117
	v_mov_b32_e32 v117, v102
	v_mov_b32_e32 v102, v119
	v_mov_b32_e32 v119, v104
	v_mov_b32_e32 v104, v113
	v_mov_b32_e32 v113, v106
	v_mov_b32_e32 v106, v115
	v_mov_b32_e32 v115, v128
	v_mov_b32_e32 v128, v203
	v_mov_b32_e32 v203, v130
	v_mov_b32_e32 v130, v205
	v_pk_mul_f32 v[64:65], v[160:161], v[64:65]
	v_pk_mul_f32 v[66:67], v[158:159], v[66:67]
	v_mov_b32_e32 v110, v88
	v_mov_b32_e32 v88, v90
	v_mov_b32_e32 v90, v84
	v_mov_b32_e32 v84, v86
	v_mov_b32_e32 v86, v80
	v_mov_b32_e32 v80, v82
	v_mov_b32_e32 v82, v124
	v_mov_b32_e32 v124, v126
	v_mov_b32_e32 v126, v120
	v_mov_b32_e32 v120, v122
	v_mov_b32_e32 v122, v116
	v_mov_b32_e32 v116, v118
	v_mov_b32_e32 v118, v112
	v_mov_b32_e32 v112, v114
	v_mov_b32_e32 v114, v202
	v_mov_b32_e32 v202, v204
	s_waitcnt lgkmcnt(12)
	v_mov_b32_e32 v205, v132
	v_mov_b32_e32 v132, v207
	v_mov_b32_e32 v207, v134
	v_mov_b32_e32 v134, v209
	v_pk_mul_f32 v[68:69], v[164:165], v[68:69]
	v_pk_mul_f32 v[70:71], v[162:163], v[70:71]
	v_pk_mul_f32 v[72:73], v[168:169], v[72:73]
	v_pk_mul_f32 v[74:75], v[166:167], v[74:75]
	v_pk_mul_f32 v[76:77], v[172:173], v[76:77]
	v_pk_mul_f32 v[78:79], v[170:171], v[78:79]
	v_pk_mul_f32 v[92:93], v[160:161], v[92:93]
	v_pk_mul_f32 v[94:95], v[158:159], v[94:95]
	v_pk_mul_f32 v[96:97], v[164:165], v[96:97]
	v_pk_mul_f32 v[98:99], v[162:163], v[98:99]
	v_pk_mul_f32 v[128:129], v[160:161], v[128:129]
	v_pk_mul_f32 v[130:131], v[158:159], v[130:131]
	v_pk_fma_f32 v[64:65], v[174:175], v[210:211], v[64:65]
	v_pk_fma_f32 v[66:67], v[176:177], v[108:109], v[66:67]
	v_mov_b32_e32 v204, v206
	v_mov_b32_e32 v206, v208
	s_waitcnt lgkmcnt(10)
	v_mov_b32_e32 v209, v136
	v_mov_b32_e32 v136, v149
	v_mov_b32_e32 v149, v138
	v_mov_b32_e32 v138, v151
	s_waitcnt lgkmcnt(8)
	v_mov_b32_e32 v151, v140
	v_mov_b32_e32 v140, v145
	v_mov_b32_e32 v145, v142
	v_mov_b32_e32 v142, v147
	s_waitcnt lgkmcnt(6)
	v_mov_b32_e32 v147, v218
	v_mov_b32_e32 v218, v215
	v_mov_b32_e32 v215, v220
	v_mov_b32_e32 v220, v217
	v_pk_mul_f32 v[100:101], v[168:169], v[100:101]
	v_pk_mul_f32 v[102:103], v[166:167], v[102:103]
	v_pk_mul_f32 v[132:133], v[164:165], v[132:133]
	v_pk_mul_f32 v[134:135], v[162:163], v[134:135]
	v_pk_fma_f32 v[68:69], v[178:179], v[110:111], v[68:69]
	v_pk_fma_f32 v[70:71], v[180:181], v[88:89], v[70:71]
	v_pk_fma_f32 v[72:73], v[182:183], v[90:91], v[72:73]
	v_pk_fma_f32 v[74:75], v[184:185], v[84:85], v[74:75]
	v_pk_fma_f32 v[76:77], v[186:187], v[86:87], v[76:77]
	v_pk_fma_f32 v[78:79], v[188:189], v[80:81], v[78:79]
	v_pk_fma_f32 v[80:81], v[174:175], v[82:83], v[92:93]
	v_pk_fma_f32 v[82:83], v[176:177], v[124:125], v[94:95]
	v_pk_fma_f32 v[84:85], v[178:179], v[126:127], v[96:97]
	v_pk_fma_f32 v[86:87], v[180:181], v[120:121], v[98:99]
	v_pk_fma_f32 v[96:97], v[174:175], v[114:115], v[128:129]
	v_pk_fma_f32 v[98:99], v[176:177], v[202:203], v[130:131]
	v_pk_add_f32 v[64:65], v[64:65], v[66:67]
	v_mov_b32_e32 v208, v148
	v_mov_b32_e32 v148, v150
	v_mov_b32_e32 v150, v144
	v_mov_b32_e32 v144, v146
	v_mov_b32_e32 v146, v214
	v_mov_b32_e32 v214, v216
	s_waitcnt lgkmcnt(4)
	v_mov_b32_e32 v217, v226
	v_mov_b32_e32 v226, v223
	v_mov_b32_e32 v223, v228
	v_mov_b32_e32 v228, v225
	v_pk_mul_f32 v[104:105], v[172:173], v[104:105]
	v_pk_mul_f32 v[106:107], v[170:171], v[106:107]
	v_pk_mul_f32 v[136:137], v[168:169], v[136:137]
	v_pk_mul_f32 v[138:139], v[166:167], v[138:139]
	v_pk_mul_f32 v[218:219], v[160:161], v[218:219]
	v_pk_mul_f32 v[220:221], v[158:159], v[220:221]
	v_pk_fma_f32 v[88:89], v[182:183], v[122:123], v[100:101]
	v_pk_fma_f32 v[90:91], v[184:185], v[116:117], v[102:103]
	v_pk_fma_f32 v[100:101], v[178:179], v[204:205], v[132:133]
	v_pk_fma_f32 v[102:103], v[180:181], v[206:207], v[134:135]
	v_pk_add_f32 v[66:67], v[68:69], v[70:71]
	v_pk_add_f32 v[68:69], v[72:73], v[74:75]
	v_pk_add_f32 v[72:73], v[80:81], v[82:83]
	v_pk_add_f32 v[80:81], v[96:97], v[98:99]
	v_pk_add_f32 v[64:65], v[64:65], 0 op_sel_hi:[1,0]
	v_mov_b32_e32 v216, v222
	v_mov_b32_e32 v222, v224
	s_waitcnt lgkmcnt(2)
	v_mov_b32_e32 v225, v234
	v_mov_b32_e32 v234, v231
	v_mov_b32_e32 v231, v236
	v_mov_b32_e32 v236, v233
	v_pk_mul_f32 v[140:141], v[172:173], v[140:141]
	v_pk_mul_f32 v[142:143], v[170:171], v[142:143]
	v_pk_mul_f32 v[226:227], v[164:165], v[226:227]
	v_pk_mul_f32 v[228:229], v[162:163], v[228:229]
	v_pk_fma_f32 v[92:93], v[186:187], v[118:119], v[104:105]
	v_pk_fma_f32 v[94:95], v[188:189], v[112:113], v[106:107]
	v_pk_fma_f32 v[104:105], v[182:183], v[208:209], v[136:137]
	v_pk_fma_f32 v[106:107], v[184:185], v[148:149], v[138:139]
	v_pk_fma_f32 v[112:113], v[174:175], v[146:147], v[218:219]
	v_pk_fma_f32 v[114:115], v[176:177], v[214:215], v[220:221]
	v_pk_add_f32 v[74:75], v[84:85], v[86:87]
	v_pk_add_f32 v[82:83], v[100:101], v[102:103]
	v_pk_add_f32 v[72:73], v[72:73], 0 op_sel_hi:[1,0]
	v_pk_add_f32 v[80:81], v[80:81], 0 op_sel_hi:[1,0]
	v_pk_add_f32 v[64:65], v[64:65], v[66:67]
	v_mov_b32_e32 v224, v230
	v_mov_b32_e32 v230, v232
	s_waitcnt lgkmcnt(0)
	v_mov_b32_e32 v233, v242
	v_mov_b32_e32 v242, v239
	v_mov_b32_e32 v239, v244
	v_mov_b32_e32 v244, v241
	v_pk_mul_f32 v[234:235], v[168:169], v[234:235]
	v_pk_mul_f32 v[236:237], v[166:167], v[236:237]
	v_pk_fma_f32 v[108:109], v[186:187], v[150:151], v[140:141]
	v_pk_fma_f32 v[110:111], v[188:189], v[144:145], v[142:143]
	v_pk_fma_f32 v[116:117], v[178:179], v[216:217], v[226:227]
	v_pk_fma_f32 v[118:119], v[180:181], v[222:223], v[228:229]
	v_pk_add_f32 v[70:71], v[76:77], v[78:79]
	v_pk_add_f32 v[76:77], v[88:89], v[90:91]
	v_pk_add_f32 v[84:85], v[104:105], v[106:107]
	v_pk_add_f32 v[88:89], v[112:113], v[114:115]
	v_pk_add_f32 v[66:67], v[72:73], v[74:75]
	v_pk_add_f32 v[72:73], v[80:81], v[82:83]
	v_pk_add_f32 v[64:65], v[64:65], v[68:69]
	v_mov_b32_e32 v232, v238
	v_mov_b32_e32 v238, v240
	v_pk_mul_f32 v[240:241], v[172:173], v[242:243]
	v_pk_mul_f32 v[242:243], v[170:171], v[244:245]
	v_pk_fma_f32 v[120:121], v[182:183], v[224:225], v[234:235]
	v_pk_fma_f32 v[122:123], v[184:185], v[230:231], v[236:237]
	v_pk_add_f32 v[78:79], v[92:93], v[94:95]
	v_pk_add_f32 v[86:87], v[108:109], v[110:111]
	v_pk_add_f32 v[90:91], v[116:117], v[118:119]
	v_pk_add_f32 v[88:89], v[88:89], 0 op_sel_hi:[1,0]
	v_pk_add_f32 v[66:67], v[66:67], v[76:77]
	v_pk_add_f32 v[68:69], v[72:73], v[84:85]
	v_pk_add_f32 v[64:65], v[64:65], v[70:71]
	v_pk_fma_f32 v[124:125], v[186:187], v[232:233], v[240:241]
	v_pk_fma_f32 v[126:127], v[188:189], v[238:239], v[242:243]
	v_pk_add_f32 v[92:93], v[120:121], v[122:123]
	v_pk_add_f32 v[74:75], v[88:89], v[90:91]
	v_pk_add_f32 v[66:67], v[66:67], v[78:79]
	v_pk_add_f32 v[68:69], v[68:69], v[86:87]
	v_add_f32_e32 v64, v64, v65
	v_pk_add_f32 v[94:95], v[124:125], v[126:127]
	v_pk_add_f32 v[72:73], v[74:75], v[92:93]
	v_add_f32_e32 v65, v66, v67
	v_add_f32_e32 v66, v68, v69
	v_pk_add_f32 v[70:71], v[72:73], v[94:95]
	v_add_f32_e32 v67, v70, v71
	v_add_f32_dpp v64, v64, v64 quad_perm:[1,0,3,2] row_mask:0xf bank_mask:0xf
	v_add_f32_dpp v65, v65, v65 quad_perm:[1,0,3,2] row_mask:0xf bank_mask:0xf
	v_add_f32_dpp v66, v66, v66 quad_perm:[1,0,3,2] row_mask:0xf bank_mask:0xf
	v_add_f32_dpp v67, v67, v67 quad_perm:[1,0,3,2] row_mask:0xf bank_mask:0xf
	v_add_f32_dpp v64, v64, v64 quad_perm:[2,3,0,1] row_mask:0xf bank_mask:0xf
	v_add_f32_dpp v65, v65, v65 quad_perm:[2,3,0,1] row_mask:0xf bank_mask:0xf
	v_add_f32_dpp v66, v66, v66 quad_perm:[2,3,0,1] row_mask:0xf bank_mask:0xf
	v_add_f32_dpp v67, v67, v67 quad_perm:[2,3,0,1] row_mask:0xf bank_mask:0xf
	v_add_f32_dpp v64, v64, v64 row_half_mirror row_mask:0xf bank_mask:0xf
	v_add_f32_dpp v65, v65, v65 row_half_mirror row_mask:0xf bank_mask:0xf
	v_add_f32_dpp v66, v66, v66 row_half_mirror row_mask:0xf bank_mask:0xf
	v_add_f32_dpp v67, v67, v67 row_half_mirror row_mask:0xf bank_mask:0xf
	v_add_f32_dpp v64, v64, v64 row_mirror row_mask:0xf bank_mask:0xf
	v_add_f32_dpp v65, v65, v65 row_mirror row_mask:0xf bank_mask:0xf
	v_add_f32_dpp v66, v66, v66 row_mirror row_mask:0xf bank_mask:0xf
	v_add_f32_dpp v67, v67, v67 row_mirror row_mask:0xf bank_mask:0xf
	v_readlane_b32 s70, v64, 0
	v_readlane_b32 s71, v64, 16
	v_readlane_b32 s72, v64, 32
	v_readlane_b32 s73, v64, 48
	v_readlane_b32 s74, v65, 0
	v_readlane_b32 s75, v65, 16
	v_readlane_b32 s76, v65, 32
	v_readlane_b32 s77, v65, 48
	v_readlane_b32 s78, v66, 0
	v_readlane_b32 s79, v66, 16
	v_readlane_b32 s80, v66, 32
	v_readlane_b32 s81, v66, 48
	v_readlane_b32 s82, v67, 0
	v_readlane_b32 s83, v67, 16
	v_readlane_b32 s84, v67, 32
	v_readlane_b32 s85, v67, 48
	v_mov_b32_e32 v68, s70
	v_mov_b32_e32 v69, s74
	v_mov_b32_e32 v70, s78
	v_mov_b32_e32 v71, s82
	v_add_f32_e32 v68, s71, v68
	v_add_f32_e32 v69, s75, v69
	v_add_f32_e32 v70, s79, v70
	v_add_f32_e32 v71, s83, v71
	v_mov_b32_e32 v64, s72
	v_mov_b32_e32 v65, s76
	v_mov_b32_e32 v66, s80
	v_mov_b32_e32 v67, s84
	v_add_f32_e32 v64, s73, v64
	v_add_f32_e32 v65, s77, v65
	v_add_f32_e32 v66, s81, v66
	v_add_f32_e32 v67, s85, v67
	v_add_f32_e32 v64, v68, v64
	v_add_f32_e32 v65, v69, v65
	v_add_f32_e32 v66, v70, v66
	v_add_f32_e32 v67, v71, v67
	s_or_b32 s10, s9, 1
	v_cmp_eq_u32_e64 s[0:1], 0, v200
	s_nop 0
	s_or_b32 s11, s9, 2
	v_cndmask_b32_e64 v64, v199, v64, s[0:1]
	v_cmp_eq_u32_e64 s[0:1], s10, v190
	s_nop 0
	s_or_b32 s12, s9, 3
	v_cndmask_b32_e64 v64, v64, v65, s[0:1]
	v_cmp_eq_u32_e64 s[0:1], s11, v190
	s_nop 0
	s_add_i32 s9, s9, 4
	v_cndmask_b32_e64 v64, v64, v66, s[0:1]
	v_cmp_eq_u32_e64 s[0:1], s12, v190
	v_add_u32_e32 v201, 0x8000, v201
	s_cmp_lg_u32 s9, 8
	v_add_u32_e32 v200, -4, v200
	v_cndmask_b32_e64 v199, v64, v67, s[0:1]
	s_cbranch_scc1 .LBB0_304
	s_and_saveexec_b64 s[0:1], vcc
	s_cbranch_execz .LBB0_302
	s_lshl_b64 s[4:5], s[4:5], 6
	v_lshl_add_u64 v[64:65], v[156:157], 0, s[4:5]
	global_store_dword v[64:65], v199, off
	s_branch .LBB0_302

.LBB0_1473:
	ds_read_b128 v[108:111], v201
	ds_read_b128 v[64:67], v201 offset:16
	ds_read_b128 v[88:91], v201 offset:2048
	ds_read_b128 v[68:71], v201 offset:2064
	ds_read_b128 v[84:87], v201 offset:4096
	ds_read_b128 v[72:75], v201 offset:4112
	ds_read_b128 v[80:83], v201 offset:6144
	ds_read_b128 v[76:79], v201 offset:6160
	ds_read_b128 v[124:127], v201 offset:8192
	ds_read_b128 v[92:95], v201 offset:8208
	ds_read_b128 v[120:123], v201 offset:10240
	ds_read_b128 v[96:99], v201 offset:10256
	ds_read_b128 v[116:119], v201 offset:12288
	ds_read_b128 v[100:103], v201 offset:12304
	ds_read_b128 v[112:115], v201 offset:14336
	ds_read_b128 v[104:107], v201 offset:14352
	ds_read_b128 v[202:205], v201 offset:16384
	ds_read_b128 v[128:131], v201 offset:16400
	ds_read_b128 v[206:209], v201 offset:18432
	ds_read_b128 v[132:135], v201 offset:18448
	ds_read_b128 v[148:151], v201 offset:20480
	ds_read_b128 v[136:139], v201 offset:20496
	ds_read_b128 v[144:147], v201 offset:22528
	ds_read_b128 v[140:143], v201 offset:22544
	s_waitcnt lgkmcnt(14)
	v_mov_b32_e32 v211, v64
	v_mov_b32_e32 v64, v109
	v_mov_b32_e32 v109, v66
	v_mov_b32_e32 v66, v111
	ds_read_b128 v[214:217], v201 offset:24576
	ds_read_b128 v[218:221], v201 offset:24592
	ds_read_b128 v[222:225], v201 offset:26624
	ds_read_b128 v[226:229], v201 offset:26640
	ds_read_b128 v[230:233], v201 offset:28672
	ds_read_b128 v[234:237], v201 offset:28688
	ds_read_b128 v[238:241], v201 offset:30720
	ds_read_b128 v[242:245], v201 offset:30736
	v_mov_b32_e32 v210, v108
	v_mov_b32_e32 v108, v110
	v_mov_b32_e32 v111, v68
	v_mov_b32_e32 v68, v89
	v_mov_b32_e32 v89, v70
	v_mov_b32_e32 v70, v91
	v_mov_b32_e32 v91, v72
	v_mov_b32_e32 v72, v85
	v_mov_b32_e32 v85, v74
	v_mov_b32_e32 v74, v87
	v_mov_b32_e32 v87, v76
	v_mov_b32_e32 v76, v81
	v_mov_b32_e32 v81, v78
	v_mov_b32_e32 v78, v83
	v_mov_b32_e32 v83, v92
	v_mov_b32_e32 v92, v125
	v_mov_b32_e32 v125, v94
	v_mov_b32_e32 v94, v127
	s_waitcnt lgkmcnt(14)
	v_mov_b32_e32 v127, v96
	v_mov_b32_e32 v96, v121
	v_mov_b32_e32 v121, v98
	v_mov_b32_e32 v98, v123
	v_mov_b32_e32 v123, v100
	v_mov_b32_e32 v100, v117
	v_mov_b32_e32 v117, v102
	v_mov_b32_e32 v102, v119
	v_mov_b32_e32 v119, v104
	v_mov_b32_e32 v104, v113
	v_mov_b32_e32 v113, v106
	v_mov_b32_e32 v106, v115
	v_mov_b32_e32 v115, v128
	v_mov_b32_e32 v128, v203
	v_mov_b32_e32 v203, v130
	v_mov_b32_e32 v130, v205
	v_pk_mul_f32 v[64:65], v[160:161], v[64:65]
	v_pk_mul_f32 v[66:67], v[158:159], v[66:67]
	v_mov_b32_e32 v110, v88
	v_mov_b32_e32 v88, v90
	v_mov_b32_e32 v90, v84
	v_mov_b32_e32 v84, v86
	v_mov_b32_e32 v86, v80
	v_mov_b32_e32 v80, v82
	v_mov_b32_e32 v82, v124
	v_mov_b32_e32 v124, v126
	v_mov_b32_e32 v126, v120
	v_mov_b32_e32 v120, v122
	v_mov_b32_e32 v122, v116
	v_mov_b32_e32 v116, v118
	v_mov_b32_e32 v118, v112
	v_mov_b32_e32 v112, v114
	v_mov_b32_e32 v114, v202
	v_mov_b32_e32 v202, v204
	s_waitcnt lgkmcnt(12)
	v_mov_b32_e32 v205, v132
	v_mov_b32_e32 v132, v207
	v_mov_b32_e32 v207, v134
	v_mov_b32_e32 v134, v209
	v_pk_mul_f32 v[68:69], v[164:165], v[68:69]
	v_pk_mul_f32 v[70:71], v[162:163], v[70:71]
	v_pk_mul_f32 v[72:73], v[168:169], v[72:73]
	v_pk_mul_f32 v[74:75], v[166:167], v[74:75]
	v_pk_mul_f32 v[76:77], v[172:173], v[76:77]
	v_pk_mul_f32 v[78:79], v[170:171], v[78:79]
	v_pk_mul_f32 v[92:93], v[160:161], v[92:93]
	v_pk_mul_f32 v[94:95], v[158:159], v[94:95]
	v_pk_mul_f32 v[96:97], v[164:165], v[96:97]
	v_pk_mul_f32 v[98:99], v[162:163], v[98:99]
	v_pk_mul_f32 v[128:129], v[160:161], v[128:129]
	v_pk_mul_f32 v[130:131], v[158:159], v[130:131]
	v_pk_fma_f32 v[64:65], v[174:175], v[210:211], v[64:65]
	v_pk_fma_f32 v[66:67], v[176:177], v[108:109], v[66:67]
	v_mov_b32_e32 v204, v206
	v_mov_b32_e32 v206, v208
	s_waitcnt lgkmcnt(10)
	v_mov_b32_e32 v209, v136
	v_mov_b32_e32 v136, v149
	v_mov_b32_e32 v149, v138
	v_mov_b32_e32 v138, v151
	s_waitcnt lgkmcnt(8)
	v_mov_b32_e32 v151, v140
	v_mov_b32_e32 v140, v145
	v_mov_b32_e32 v145, v142
	v_mov_b32_e32 v142, v147
	s_waitcnt lgkmcnt(6)
	v_mov_b32_e32 v147, v218
	v_mov_b32_e32 v218, v215
	v_mov_b32_e32 v215, v220
	v_mov_b32_e32 v220, v217
	v_pk_mul_f32 v[100:101], v[168:169], v[100:101]
	v_pk_mul_f32 v[102:103], v[166:167], v[102:103]
	v_pk_mul_f32 v[132:133], v[164:165], v[132:133]
	v_pk_mul_f32 v[134:135], v[162:163], v[134:135]
	v_pk_fma_f32 v[68:69], v[178:179], v[110:111], v[68:69]
	v_pk_fma_f32 v[70:71], v[180:181], v[88:89], v[70:71]
	v_pk_fma_f32 v[72:73], v[182:183], v[90:91], v[72:73]
	v_pk_fma_f32 v[74:75], v[184:185], v[84:85], v[74:75]
	v_pk_fma_f32 v[76:77], v[186:187], v[86:87], v[76:77]
	v_pk_fma_f32 v[78:79], v[188:189], v[80:81], v[78:79]
	v_pk_fma_f32 v[80:81], v[174:175], v[82:83], v[92:93]
	v_pk_fma_f32 v[82:83], v[176:177], v[124:125], v[94:95]
	v_pk_fma_f32 v[84:85], v[178:179], v[126:127], v[96:97]
	v_pk_fma_f32 v[86:87], v[180:181], v[120:121], v[98:99]
	v_pk_fma_f32 v[96:97], v[174:175], v[114:115], v[128:129]
	v_pk_fma_f32 v[98:99], v[176:177], v[202:203], v[130:131]
	v_pk_add_f32 v[64:65], v[64:65], v[66:67]
	v_mov_b32_e32 v208, v148
	v_mov_b32_e32 v148, v150
	v_mov_b32_e32 v150, v144
	v_mov_b32_e32 v144, v146
	v_mov_b32_e32 v146, v214
	v_mov_b32_e32 v214, v216
	s_waitcnt lgkmcnt(4)
	v_mov_b32_e32 v217, v226
	v_mov_b32_e32 v226, v223
	v_mov_b32_e32 v223, v228
	v_mov_b32_e32 v228, v225
	v_pk_mul_f32 v[104:105], v[172:173], v[104:105]
	v_pk_mul_f32 v[106:107], v[170:171], v[106:107]
	v_pk_mul_f32 v[136:137], v[168:169], v[136:137]
	v_pk_mul_f32 v[138:139], v[166:167], v[138:139]
	v_pk_mul_f32 v[218:219], v[160:161], v[218:219]
	v_pk_mul_f32 v[220:221], v[158:159], v[220:221]
	v_pk_fma_f32 v[88:89], v[182:183], v[122:123], v[100:101]
	v_pk_fma_f32 v[90:91], v[184:185], v[116:117], v[102:103]
	v_pk_fma_f32 v[100:101], v[178:179], v[204:205], v[132:133]
	v_pk_fma_f32 v[102:103], v[180:181], v[206:207], v[134:135]
	v_pk_add_f32 v[66:67], v[68:69], v[70:71]
	v_pk_add_f32 v[68:69], v[72:73], v[74:75]
	v_pk_add_f32 v[72:73], v[80:81], v[82:83]
	v_pk_add_f32 v[80:81], v[96:97], v[98:99]
	v_pk_add_f32 v[64:65], v[64:65], 0 op_sel_hi:[1,0]
	v_mov_b32_e32 v216, v222
	v_mov_b32_e32 v222, v224
	s_waitcnt lgkmcnt(2)
	v_mov_b32_e32 v225, v234
	v_mov_b32_e32 v234, v231
	v_mov_b32_e32 v231, v236
	v_mov_b32_e32 v236, v233
	v_pk_mul_f32 v[140:141], v[172:173], v[140:141]
	v_pk_mul_f32 v[142:143], v[170:171], v[142:143]
	v_pk_mul_f32 v[226:227], v[164:165], v[226:227]
	v_pk_mul_f32 v[228:229], v[162:163], v[228:229]
	v_pk_fma_f32 v[92:93], v[186:187], v[118:119], v[104:105]
	v_pk_fma_f32 v[94:95], v[188:189], v[112:113], v[106:107]
	v_pk_fma_f32 v[104:105], v[182:183], v[208:209], v[136:137]
	v_pk_fma_f32 v[106:107], v[184:185], v[148:149], v[138:139]
	v_pk_fma_f32 v[112:113], v[174:175], v[146:147], v[218:219]
	v_pk_fma_f32 v[114:115], v[176:177], v[214:215], v[220:221]
	v_pk_add_f32 v[74:75], v[84:85], v[86:87]
	v_pk_add_f32 v[82:83], v[100:101], v[102:103]
	v_pk_add_f32 v[72:73], v[72:73], 0 op_sel_hi:[1,0]
	v_pk_add_f32 v[80:81], v[80:81], 0 op_sel_hi:[1,0]
	v_pk_add_f32 v[64:65], v[64:65], v[66:67]
	v_mov_b32_e32 v224, v230
	v_mov_b32_e32 v230, v232
	s_waitcnt lgkmcnt(0)
	v_mov_b32_e32 v233, v242
	v_mov_b32_e32 v242, v239
	v_mov_b32_e32 v239, v244
	v_mov_b32_e32 v244, v241
	v_pk_mul_f32 v[234:235], v[168:169], v[234:235]
	v_pk_mul_f32 v[236:237], v[166:167], v[236:237]
	v_pk_fma_f32 v[108:109], v[186:187], v[150:151], v[140:141]
	v_pk_fma_f32 v[110:111], v[188:189], v[144:145], v[142:143]
	v_pk_fma_f32 v[116:117], v[178:179], v[216:217], v[226:227]
	v_pk_fma_f32 v[118:119], v[180:181], v[222:223], v[228:229]
	v_pk_add_f32 v[70:71], v[76:77], v[78:79]
	v_pk_add_f32 v[76:77], v[88:89], v[90:91]
	v_pk_add_f32 v[84:85], v[104:105], v[106:107]
	v_pk_add_f32 v[88:89], v[112:113], v[114:115]
	v_pk_add_f32 v[66:67], v[72:73], v[74:75]
	v_pk_add_f32 v[72:73], v[80:81], v[82:83]
	v_pk_add_f32 v[64:65], v[64:65], v[68:69]
	v_mov_b32_e32 v232, v238
	v_mov_b32_e32 v238, v240
	v_pk_mul_f32 v[240:241], v[172:173], v[242:243]
	v_pk_mul_f32 v[242:243], v[170:171], v[244:245]
	v_pk_fma_f32 v[120:121], v[182:183], v[224:225], v[234:235]
	v_pk_fma_f32 v[122:123], v[184:185], v[230:231], v[236:237]
	v_pk_add_f32 v[78:79], v[92:93], v[94:95]
	v_pk_add_f32 v[86:87], v[108:109], v[110:111]
	v_pk_add_f32 v[90:91], v[116:117], v[118:119]
	v_pk_add_f32 v[88:89], v[88:89], 0 op_sel_hi:[1,0]
	v_pk_add_f32 v[66:67], v[66:67], v[76:77]
	v_pk_add_f32 v[68:69], v[72:73], v[84:85]
	v_pk_add_f32 v[64:65], v[64:65], v[70:71]
	v_pk_fma_f32 v[124:125], v[186:187], v[232:233], v[240:241]
	v_pk_fma_f32 v[126:127], v[188:189], v[238:239], v[242:243]
	v_pk_add_f32 v[92:93], v[120:121], v[122:123]
	v_pk_add_f32 v[74:75], v[88:89], v[90:91]
	v_pk_add_f32 v[66:67], v[66:67], v[78:79]
	v_pk_add_f32 v[68:69], v[68:69], v[86:87]
	v_add_f32_e32 v64, v64, v65
	v_pk_add_f32 v[94:95], v[124:125], v[126:127]
	v_pk_add_f32 v[72:73], v[74:75], v[92:93]
	v_add_f32_e32 v65, v66, v67
	v_add_f32_e32 v66, v68, v69
	v_pk_add_f32 v[70:71], v[72:73], v[94:95]
	v_add_f32_e32 v67, v70, v71
	v_add_f32_dpp v64, v64, v64 quad_perm:[1,0,3,2] row_mask:0xf bank_mask:0xf
	v_add_f32_dpp v65, v65, v65 quad_perm:[1,0,3,2] row_mask:0xf bank_mask:0xf
	v_add_f32_dpp v66, v66, v66 quad_perm:[1,0,3,2] row_mask:0xf bank_mask:0xf
	v_add_f32_dpp v67, v67, v67 quad_perm:[1,0,3,2] row_mask:0xf bank_mask:0xf
	v_add_f32_dpp v64, v64, v64 quad_perm:[2,3,0,1] row_mask:0xf bank_mask:0xf
	v_add_f32_dpp v65, v65, v65 quad_perm:[2,3,0,1] row_mask:0xf bank_mask:0xf
	v_add_f32_dpp v66, v66, v66 quad_perm:[2,3,0,1] row_mask:0xf bank_mask:0xf
	v_add_f32_dpp v67, v67, v67 quad_perm:[2,3,0,1] row_mask:0xf bank_mask:0xf
	v_add_f32_dpp v64, v64, v64 row_half_mirror row_mask:0xf bank_mask:0xf
	v_add_f32_dpp v65, v65, v65 row_half_mirror row_mask:0xf bank_mask:0xf
	v_add_f32_dpp v66, v66, v66 row_half_mirror row_mask:0xf bank_mask:0xf
	v_add_f32_dpp v67, v67, v67 row_half_mirror row_mask:0xf bank_mask:0xf
	v_add_f32_dpp v64, v64, v64 row_mirror row_mask:0xf bank_mask:0xf
	v_add_f32_dpp v65, v65, v65 row_mirror row_mask:0xf bank_mask:0xf
	v_add_f32_dpp v66, v66, v66 row_mirror row_mask:0xf bank_mask:0xf
	v_add_f32_dpp v67, v67, v67 row_mirror row_mask:0xf bank_mask:0xf
	v_readlane_b32 s70, v64, 0
	v_readlane_b32 s71, v64, 16
	v_readlane_b32 s72, v64, 32
	v_readlane_b32 s73, v64, 48
	v_readlane_b32 s74, v65, 0
	v_readlane_b32 s75, v65, 16
	v_readlane_b32 s76, v65, 32
	v_readlane_b32 s77, v65, 48
	v_readlane_b32 s78, v66, 0
	v_readlane_b32 s79, v66, 16
	v_readlane_b32 s80, v66, 32
	v_readlane_b32 s81, v66, 48
	v_readlane_b32 s82, v67, 0
	v_readlane_b32 s83, v67, 16
	v_readlane_b32 s84, v67, 32
	v_readlane_b32 s85, v67, 48
	v_mov_b32_e32 v68, s70
	v_mov_b32_e32 v69, s74
	v_mov_b32_e32 v70, s78
	v_mov_b32_e32 v71, s82
	v_add_f32_e32 v68, s71, v68
	v_add_f32_e32 v69, s75, v69
	v_add_f32_e32 v70, s79, v70
	v_add_f32_e32 v71, s83, v71
	v_mov_b32_e32 v64, s72
	v_mov_b32_e32 v65, s76
	v_mov_b32_e32 v66, s80
	v_mov_b32_e32 v67, s84
	v_add_f32_e32 v64, s73, v64
	v_add_f32_e32 v65, s77, v65
	v_add_f32_e32 v66, s81, v66
	v_add_f32_e32 v67, s85, v67
	v_add_f32_e32 v64, v68, v64
	v_add_f32_e32 v65, v69, v65
	v_add_f32_e32 v66, v70, v66
	v_add_f32_e32 v67, v71, v67
	s_or_b32 s10, s9, 1
	v_cmp_eq_u32_e64 s[0:1], 0, v200
	s_nop 0
	s_or_b32 s11, s9, 2
	v_cndmask_b32_e64 v64, v199, v64, s[0:1]
	v_cmp_eq_u32_e64 s[0:1], s10, v190
	s_nop 0
	s_or_b32 s12, s9, 3
	v_cndmask_b32_e64 v64, v64, v65, s[0:1]
	v_cmp_eq_u32_e64 s[0:1], s11, v190
	s_nop 0
	s_add_i32 s9, s9, 4
	v_cndmask_b32_e64 v64, v64, v66, s[0:1]
	v_cmp_eq_u32_e64 s[0:1], s12, v190
	v_add_u32_e32 v201, 0x8000, v201
	s_cmp_lg_u32 s9, 16
	v_add_u32_e32 v200, -4, v200
	v_cndmask_b32_e64 v199, v64, v67, s[0:1]
	s_cbranch_scc1 .LBB0_1473
	s_and_saveexec_b64 s[0:1], vcc
	s_cbranch_execz .LBB0_1471
	s_lshl_b64 s[4:5], s[4:5], 6
	v_lshl_add_u64 v[64:65], v[156:157], 0, s[4:5]
	global_store_dword v[64:65], v199, off
	s_branch .LBB0_1471
